# RMS-norm-2 scale derived at FFN1 entry from the W_out epilogue's partial sums (one row per thread); the separate NORM2 phase and its grid barrier removed
# speedup vs baseline: 1.0072x; 1.0056x over previous
; __device__ __forceinline__ int lane_now() { int l; asm volatile("v_mbcnt_lo_u32_b32 %0, -1, 0\n\tv_mbcnt_hi_u32_b32 %0, -1, %0" : "=v"(l)); return l; }
; __device__ __forceinline__ void ph_norm2(Ctx& C) {
;     const int lane = lane_now(); const float* pp = (const float*)(C.ws + WS_SSQP); float* rs = (float*)(C.ws + WS_RSTD);
;     for (int row = C.gw * 64 + lane; row < S; row += C.ngw * 64) { const f32x4* p = (const f32x4*)(pp + (size_t)row * 32); float ss = 0.f;
; #pragma unroll
;         for (int q = 0; q < 8; ++q) { const f32x4 v = p[q]; ss += (v[0] + v[1]) + (v[2] + v[3]); }
;         rs[row] = 1.0f / sqrtf(ss * (1.0f / D) + 1e-6f); }
; }
.LBB0_1418:
	s_branch .LBB0_1479
	s_load_dword s0, s[88:89], 0xd8
	s_waitcnt lgkmcnt(0)
	s_cmp_gt_i32 s0, 13
	s_cbranch_scc1 .LBB0_1479
	s_load_dword s0, s[88:89], 0xdc
	s_waitcnt lgkmcnt(0)
	s_cmp_lt_i32 s0, 14
	s_cbranch_scc1 .LBB0_1479
	v_readlane_b32 s0, v231, 1
	v_readlane_b32 s1, v231, 2
	s_load_dwordx2 s[4:5], s[88:89], 0xd0
	s_lshl_b32 s2, s92, 6
	s_load_dword s0, s[0:1], 0xe0
	v_readlane_b32 s1, v231, 0
	s_lshl_b32 s1, s1, 9
	v_mbcnt_lo_u32_b32 v0, -1, 0
	v_mbcnt_hi_u32_b32 v0, -1, v0
	s_add_i32 s2, s2, s1
	v_add_u32_e32 v0, s2, v0
	s_movk_i32 s1, 0x4000
	v_cmp_gt_i32_e32 vcc, s1, v0
	s_and_saveexec_b64 s[6:7], vcc
	s_cbranch_execz .LBB0_1423
	s_waitcnt lgkmcnt(0)
	s_lshl_b32 s8, s0, 9
	v_ashrrev_i32_e32 v1, 31, v0
	v_mov_b64_e32 v[2:3], 0x1e600000
	s_ashr_i32 s9, s8, 31
	v_lshl_add_u64 v[2:3], v[0:1], 2, v[2:3]
	s_lshl_b64 s[10:11], s[8:9], 2
	v_lshlrev_b64 v[4:5], 7, v[0:1]
	s_lshl_b64 s[12:13], s[8:9], 7
	s_mov_b64 s[14:15], 0
	s_mov_b64 s[16:17], 0x1e400000
	s_mov_b64 s[18:19], 0x1e400040
	v_mov_b32_e32 v1, 0x358637bd
	s_mov_b32 s1, 0xf800000
	v_mov_b32_e32 v6, 0x260
	s_movk_i32 s9, 0x3fff

; template <class Epi> __device__ __forceinline__ void gemm8(Ctx& C, const bf16* A, const bf16* Bt, int N, int K, const Epi& E) {
;     asm volatile("" : "+s"(N), "+s"(K));
;     pg8::Gemm g{A, Bt, S, N, K}; pg8::StaticOrder so; so.init(S, N, C.nb, C.bid);
;     pg8::gemm_phase<Epi, pg8::StaticOrder, true, true>(C.lds, g, so, E, C.wave);
; __device__ __forceinline__ void ph_norm2(Ctx& C) {
;     ...
;     for (int row = C.gw * 64 + lane; row < S; row += C.ngw * 64) { const f32x4* p = (const f32x4*)(pp + (size_t)row * 32); float ss = 0.f;
; #pragma unroll
;         for (int q = 0; q < 8; ++q) { const f32x4 v = p[q]; ss += (v[0] + v[1]) + (v[2] + v[3]); }
;         rs[row] = 1.0f / sqrtf(ss * (1.0f / D) + 1e-6f); }
.LBB0_1479:
	s_mov_b32 s101, 0
	s_load_dword s0, s[88:89], 0xd8
	s_waitcnt lgkmcnt(0)
	s_cmp_gt_i32 s0, 14
	s_cbranch_scc1 .LBB0_1558
	s_load_dword s0, s[88:89], 0xdc
	s_waitcnt lgkmcnt(0)
	s_cmp_lt_i32 s0, 15
	s_cbranch_scc1 .LBB0_1558
	s_load_dwordx2 s[4:5], s[88:89], 0xd0
	v_readlane_b32 s0, v231, 0
	v_mbcnt_lo_u32_b32 v0, -1, 0
	v_mbcnt_hi_u32_b32 v0, -1, v0
	s_nop 3
	s_and_b32 s1, s0, 7
	s_lshr_b32 s0, s0, 3
	s_and_b32 s0, s0, 3
	s_lshl_b32 s1, s1, 3
	s_add_i32 s0, s0, s1
	s_lshr_b32 s1, s92, 2
	s_lshl_b32 s1, s1, 2
	s_add_i32 s0, s0, s1
	s_lshl_b32 s0, s0, 8
	s_and_b32 s1, s92, 3
	s_lshl_b32 s1, s1, 6
	s_add_i32 s0, s0, s1
	v_add_u32_e32 v0, s0, v0
	v_lshlrev_b32_e32 v2, 7, v0
	v_mov_b32_e32 v3, 0
	s_waitcnt lgkmcnt(0)
	v_lshl_add_u64 v[2:3], s[4:5], 0, v[2:3]
	s_mov_b64 s[6:7], 0x1e400000
	v_lshl_add_u64 v[2:3], v[2:3], 0, s[6:7]
	global_load_dwordx4 v[4:7], v[2:3], off
	global_load_dwordx4 v[8:11], v[2:3], off offset:16
	global_load_dwordx4 v[12:15], v[2:3], off offset:32
	global_load_dwordx4 v[16:19], v[2:3], off offset:48
	global_load_dwordx4 v[20:23], v[2:3], off offset:64
	global_load_dwordx4 v[24:27], v[2:3], off offset:80
	global_load_dwordx4 v[28:31], v[2:3], off offset:96
	global_load_dwordx4 v[32:35], v[2:3], off offset:112
	v_mov_b32_e32 v36, 0
	s_waitcnt vmcnt(7)
	v_add_f32_e32 v37, v4, v5
	v_add_f32_e32 v38, v6, v7
	v_add_f32_e32 v37, v37, v38
	v_add_f32_e32 v36, v36, v37
	s_waitcnt vmcnt(6)
	v_add_f32_e32 v37, v8, v9
	v_add_f32_e32 v38, v10, v11
	v_add_f32_e32 v37, v37, v38
	v_add_f32_e32 v36, v36, v37
	s_waitcnt vmcnt(5)
	v_add_f32_e32 v37, v12, v13
	v_add_f32_e32 v38, v14, v15
	v_add_f32_e32 v37, v37, v38
	v_add_f32_e32 v36, v36, v37
	s_waitcnt vmcnt(4)
	v_add_f32_e32 v37, v16, v17
	v_add_f32_e32 v38, v18, v19
	v_add_f32_e32 v37, v37, v38
	v_add_f32_e32 v36, v36, v37
	s_waitcnt vmcnt(3)
	v_add_f32_e32 v37, v20, v21
	v_add_f32_e32 v38, v22, v23
	v_add_f32_e32 v37, v37, v38
	v_add_f32_e32 v36, v36, v37
	s_waitcnt vmcnt(2)
	v_add_f32_e32 v37, v24, v25
	v_add_f32_e32 v38, v26, v27
	v_add_f32_e32 v37, v37, v38
	v_add_f32_e32 v36, v36, v37
	s_waitcnt vmcnt(1)
	v_add_f32_e32 v37, v28, v29
	v_add_f32_e32 v38, v30, v31
	v_add_f32_e32 v37, v37, v38
	v_add_f32_e32 v36, v36, v37
	s_waitcnt vmcnt(0)
	v_add_f32_e32 v37, v32, v33
	v_add_f32_e32 v38, v34, v35
	v_add_f32_e32 v37, v37, v38
	v_add_f32_e32 v36, v36, v37
	v_mov_b32_e32 v37, 0x358637bd
	v_fmamk_f32 v36, v36, 0x3a000000, v37
	v_rsq_f32_e32 v36, v36
	v_lshlrev_b32_e32 v38, 2, v0
	v_mov_b32_e32 v39, 0
	v_lshl_add_u64 v[38:39], s[4:5], 0, v[38:39]
	s_mov_b64 s[6:7], 0x1e600000
	v_lshl_add_u64 v[38:39], v[38:39], 0, s[6:7]
	global_store_dword v[38:39], v36, off
	s_waitcnt vmcnt(0)
	s_barrier
	v_readlane_b32 s0, v231, 1
	v_readlane_b32 s1, v231, 2
	s_load_dword s48, s[0:1], 0xe0
	s_movk_i32 s0, 0x2c00
	s_movk_i32 s4, 0x800
	s_load_dwordx2 s[10:11], s[88:89], 0xd0
	s_ashr_i32 s1, s0, 31
	s_lshr_b32 s1, s1, 24
	s_add_i32 s0, s0, s1
	s_ashr_i32 s1, s0, 8
	s_lshl_b32 s2, s1, 6
	v_readlane_b32 s0, v231, 0
	s_cmp_ge_i32 s0, s2
	v_mbcnt_lo_u32_b32 v12, -1, 0
	v_mbcnt_hi_u32_b32 v12, -1, v12
	s_cbranch_scc1 .LBB0_1502
; __device__ __forceinline__ int lane_now() { int l; asm volatile("v_mbcnt_lo_u32_b32 %0, -1, 0\n\tv_mbcnt_hi_u32_b32 %0, -1, %0" : "=v"(l)); return l; }
; #define PG8_STAGE(bufoff, gbase, voff) do { _Pragma("unroll") for (int _i = 0; _i < 2; ++_i) \
;         __builtin_amdgcn_global_load_lds((const unsigned*)((const char*)(gbase) + (voff)[_i]), (PG8_LAS unsigned*)(lds + (bufoff) + ldsw + _i * 8192), 16, 0, 0); } while (0)
; template <class Epi, class Sched, bool ALIGN_EPI = false, bool SP2 = false>
; __device__ __forceinline__ void gemm_phase(PG8_LAS unsigned char* lds, const Gemm g, const Sched& S, const Epi& E, const int wid) {
;     const int lane = lane_now(), tid = wid * 64 + lane, wr = wid >> 2, wc = wid & 3, fr = lane & 15, fq = lane >> 4;
;     const int K = g.K, nt = K / BK;
;     unsigned voffA[2], voffB[2];
; #pragma unroll
;     for (int i = 0; i < 2; ++i) { int R, C; stage_rc(tid * 16 + i * 8192, R, C); const int Rb = Epi::PERM ? ((R & ~31) + perm32(R & 31)) : R;
;         voffA[i] = (unsigned)(R * K + C) * 2u; voffB[i] = (unsigned)(Rb * K + C) * 2u; }
;     const size_t kstep = (size_t)(BK * 2);
;     const size_t hstep = (size_t)HALF * K * 2;
;     const size_t tstep = 2 * hstep;
;     const unsigned ldsw = (unsigned)wid * 1024u;
;     const int aoff = lds_byte(wr * 64 + fr, fq * 8), boff = lds_byte(wc * 32 + fr, fq * 8);
;     ...
;     Unit cur, nxt; int ui = 0;
;     if (!S.next(0, cur)) return;
;     f32x4 acc[2][2][4][2];
; #pragma unroll
;     for (int a = 0; a < 2; ++a)
; #pragma unroll
;         for (int b = 0; b < 2; ++b)
; #pragma unroll
;             for (int m = 0; m < 4; ++m)
; #pragma unroll
;                 for (int n = 0; n < 2; ++n) acc[a][b][m][n] = (f32x4){0.f, 0.f, 0.f, 0.f};
;     bf16x8 At[4][2], B0[2][2], B1[2][2];
;     const char* cA = (const char*)g.A + (size_t)cur.pm * tstep; const char* cB = (const char*)g.Bt + (size_t)cur.pn * tstep;
;     S.a_ready(cur);
;     if constexpr (SP2) {
;         PG8_STAGE(PG8_SB(0, 0), cB, voffB); PG8_STAGE(PG8_SB(0, 1), cB + hstep, voffB); PG8_STAGE(PG8_SA(0, 0), cA, voffA); PG8_STAGE(PG8_SA(0, 1), cA + hstep, voffA);
;         if (wr == 1) PG8_BAR;
;         PG8_WAIT_V(2); PG8_BAR;
;         PG8_STAGE(PG8_SB(1, 0), cB + kstep, voffB); PG8_STAGE(PG8_SA(1, 0), cA + kstep, voffA); PG8_STAGE(PG8_SB(1, 1), cB + hstep + kstep, voffB);
;         PG8_WAIT_V(6); PG8_BAR;
	s_waitcnt lgkmcnt(0)
	s_add_u32 s30, s10, 0x1a400000
	s_addc_u32 s31, s11, 0
	s_add_u32 s34, s10, 0xe200000
	s_addc_u32 s35, s11, 0
	s_lshl_b32 s36, s92, 10
	v_lshl_add_u32 v0, v12, 4, s36
	v_add_u32_e32 v1, 0x2000, v0
	v_ashrrev_i32_e32 v2, 31, v1
	v_lshrrev_b32_e32 v2, 22, v2
	v_add_u32_e32 v2, v1, v2
	v_ashrrev_i32_e32 v2, 10, v2
	v_mul_i32_i24_e32 v3, 0x400, v2
	v_sub_u32_e32 v1, v1, v3
	v_lshrrev_b32_e32 v3, 4, v1
	v_bitop3_b32 v1, v3, v1, 32 bitop3:0x6c
	v_ashrrev_i32_e32 v3, 31, v1
	v_lshrrev_b32_e32 v3, 26, v3
	v_add_u32_e32 v3, v1, v3
	v_lshlrev_b32_e32 v5, 3, v2
	v_lshlrev_b32_e32 v2, 5, v2
	v_and_b32_e32 v13, 32, v2
	v_and_b32_e32 v2, 0xffc0, v3
	v_sub_u32_e32 v1, v1, v2
	v_ashrrev_i32_e32 v4, 6, v3
	v_and_b32_e32 v5, -16, v5
	v_lshrrev_b16_e32 v2, 7, v1
	v_add_u32_e32 v5, v4, v5
	v_and_b32_e32 v2, 1, v2
	v_and_b32_e32 v4, 3, v4
	s_mov_b32 s3, 0x7fffffe0
	v_lshrrev_b32_e32 v6, 2, v5
	v_lshlrev_b32_e32 v7, 1, v5
	v_add_u16_e32 v1, v1, v2
	v_mov_b32_e32 v2, 1
	v_and_or_b32 v4, v5, s3, v4
	v_and_b32_e32 v6, 4, v6
	v_and_b32_e32 v7, 24, v7
	v_ashrrev_i16_sdwa v1, v2, sext(v1) dst_sel:DWORD dst_unused:UNUSED_PAD src0_sel:DWORD src1_sel:BYTE_0
	v_or3_b32 v4, v4, v6, v7
	v_bfe_i32 v14, v1, 0, 16
	v_mul_lo_u32 v4, v4, s4
	v_add_u32_e32 v1, v13, v14
	v_mul_lo_u32 v15, v5, s4
	s_waitcnt vmcnt(0)
	v_add_lshl_u32 v128, v4, v1, 1
	v_add_lshl_u32 v130, v1, v15, 1
	v_ashrrev_i32_e32 v1, 31, v0
	v_lshrrev_b32_e32 v1, 22, v1
	v_add_u32_e32 v1, v0, v1
	v_ashrrev_i32_e32 v1, 10, v1
	v_mul_i32_i24_e32 v3, 0x400, v1
	v_sub_u32_e32 v0, v0, v3
	v_lshrrev_b32_e32 v3, 4, v0
	v_bitop3_b32 v0, v3, v0, 32 bitop3:0x6c
	v_ashrrev_i32_e32 v3, 31, v0
	v_lshrrev_b32_e32 v3, 26, v3
	v_add_u32_e32 v3, v0, v3
	v_lshlrev_b32_e32 v5, 3, v1
	v_ashrrev_i32_e32 v4, 6, v3
	v_and_b32_e32 v5, -16, v5
	v_readlane_b32 s7, v231, 0
	v_add_u32_e32 v5, v4, v5
	v_and_b32_e32 v4, 3, v4
	s_ashr_i32 s38, s7, 31
	v_and_or_b32 v4, v5, s3, v4
	s_lshr_b32 s3, s38, 29
	s_add_i32 s3, s7, s3
	s_ashr_i32 s5, s4, 31
	s_lshl_b32 s37, s1, 3
	s_ashr_i32 s6, s3, 3
	s_and_b32 s3, s3, -8
	s_ashr_i32 s0, s92, 2
	s_lshl_b64 s[12:13], s[4:5], 8
	s_lshl_b64 s[14:15], s[4:5], 9
	s_sub_i32 s3, s7, s3
	s_or_b32 s39, s37, 1
	s_cmp_lt_i32 s3, 0
	v_lshlrev_b32_e32 v1, 5, v1
	s_cselect_b32 s7, s39, s37
	s_lshl_b32 s40, s1, 2
	v_and_b32_e32 v16, 32, v1
	v_and_b32_e32 v1, 0xc0, v3
	s_abs_i32 s41, s40
	v_sub_u32_e32 v0, v0, v1
	v_cvt_f32_u32_e32 v1, s41
	s_mul_i32 s3, s7, s3
	s_sub_i32 s7, 0, s41
	s_add_i32 s3, s3, s6
	v_rcp_iflag_f32_e32 v1, v1
	s_ashr_i32 s6, s3, 31
	s_bfe_i32 s42, s1, 0x1001d
	s_xor_b32 s1, s6, s42
	v_mul_f32_e32 v1, 0x4f7ffffe, v1
	v_cvt_u32_f32_e32 v1, v1
	s_abs_i32 s6, s3
	v_lshrrev_b32_e32 v6, 2, v5
	v_lshlrev_b32_e32 v7, 1, v5
	v_readfirstlane_b32 s43, v1
	s_mul_i32 s7, s7, s43
	s_mul_hi_u32 s7, s43, s7
	s_add_i32 s43, s43, s7
	s_mul_hi_u32 s7, s6, s43
	s_mul_i32 s8, s7, s41
	s_sub_i32 s6, s6, s8
	s_add_i32 s8, s7, 1
	s_sub_i32 s9, s6, s41
	s_cmp_ge_u32 s6, s41
	s_cselect_b32 s7, s8, s7
	s_cselect_b32 s6, s9, s6
	s_add_i32 s8, s7, 1
	s_cmp_ge_u32 s6, s41
	s_cselect_b32 s6, s8, s7
	s_xor_b32 s6, s6, s1
	s_sub_i32 s1, s6, s1
	s_lshl_b32 s6, s1, 2
	s_sub_i32 s7, 64, s6
	s_min_i32 s7, s7, 4
	s_abs_i32 s8, s7
	v_cvt_f32_u32_e32 v1, s8
	v_and_b32_e32 v6, 4, v6
	v_and_b32_e32 v7, 24, v7
	v_ashrrev_i16_sdwa v0, v2, sext(v0) dst_sel:DWORD dst_unused:UNUSED_PAD src0_sel:DWORD src1_sel:BYTE_0
	v_or3_b32 v4, v4, v6, v7
	v_bfe_i32 v17, v0, 0, 16
	v_mul_lo_u32 v4, v4, s4
	v_add_u32_e32 v0, v16, v17
	v_mul_lo_u32 v18, v5, s4
	v_add_lshl_u32 v132, v4, v0, 1
	v_add_lshl_u32 v134, v0, v18, 1
	v_rcp_iflag_f32_e32 v0, v1
	s_sub_i32 s16, 0, s8
	s_mul_i32 s1, s1, s40
	s_sub_i32 s1, s3, s1
	v_mul_f32_e32 v0, 0x4f7ffffe, v0
	v_cvt_u32_f32_e32 v0, v0
	s_abs_i32 s9, s1
	s_xor_b32 s3, s1, s7
	s_ashr_i32 s3, s3, 31
	v_readfirstlane_b32 s17, v0
	s_mul_i32 s16, s16, s17
	s_mul_hi_u32 s16, s17, s16
	s_add_i32 s17, s17, s16
	s_mul_hi_u32 s16, s9, s17
	s_mul_i32 s17, s16, s8
	s_sub_i32 s9, s9, s17
	s_add_i32 s17, s16, 1
	s_sub_i32 s18, s9, s8
	s_cmp_ge_u32 s9, s8
	s_cselect_b32 s16, s17, s16
	s_cselect_b32 s9, s18, s9
	s_add_i32 s17, s16, 1
	s_cmp_ge_u32 s9, s8
	s_cselect_b32 s8, s17, s16
	s_xor_b32 s8, s8, s3
	s_sub_i32 s62, s8, s3
	s_mul_i32 s3, s62, s7
	s_sub_i32 s1, s1, s3
	s_add_i32 s63, s1, s6
	s_lshr_b64 s[6:7], s[4:5], 23
	s_ashr_i32 s1, s63, 31
	s_ashr_i32 s7, s62, 31
	s_mul_i32 s1, s14, s1
	s_mul_hi_u32 s3, s14, s63
	s_mul_i32 s7, s14, s7
	s_mul_hi_u32 s8, s14, s62
	s_add_i32 s1, s3, s1
	s_mul_i32 s3, s6, s63
	s_add_i32 s7, s8, s7
	s_mul_i32 s6, s6, s62
	s_add_i32 s1, s1, s3
	s_add_i32 s7, s7, s6
	s_mul_i32 s6, s14, s62
	s_add_u32 s6, s34, s6
	s_addc_u32 s7, s35, s7
	s_add_i32 s44, s36, 0
	s_add_i32 m0, s44, 0x10000
	s_mul_i32 s3, s14, s63
	global_load_lds_dwordx4 v132, s[6:7]
	s_add_i32 m0, s44, 0x12000
	s_add_u32 s16, s6, s12
	global_load_lds_dwordx4 v128, s[6:7]
	s_addc_u32 s17, s7, s13
	s_add_i32 m0, s44, 0x14000
	v_mov_b32_e32 v133, 0
	global_load_lds_dwordx4 v132, s[16:17]
	s_add_i32 m0, s44, 0x16000
	s_add_u32 s8, s30, s3
	s_addc_u32 s9, s31, s1
	s_add_i32 s45, s44, 0x2000
	global_load_lds_dwordx4 v128, s[16:17]
	s_mov_b32 m0, s44
	s_add_u32 s18, s8, s12
	global_load_lds_dwordx4 v134, s[8:9]
	s_mov_b32 m0, s45
	s_addc_u32 s19, s9, s13
	s_add_i32 s46, s44, 0x4000
	global_load_lds_dwordx4 v130, s[8:9]
	s_mov_b32 m0, s46
	s_add_i32 s47, s44, 0x6000
	global_load_lds_dwordx4 v134, s[18:19]
	s_mov_b32 m0, s47
	v_mov_b32_e32 v129, v133
	global_load_lds_dwordx4 v130, s[18:19]
	v_mov_b32_e32 v135, v133
	v_mov_b32_e32 v131, v133
	s_cmp_eq_u32 s0, 1
	s_mov_b32 s49, 0
	v_lshl_add_u64 v[8:9], s[6:7], 0, v[132:133]
	v_lshl_add_u64 v[4:5], s[6:7], 0, v[128:129]
	v_lshl_add_u64 v[2:3], s[16:17], 0, v[132:133]
	v_lshl_add_u64 v[0:1], s[16:17], 0, v[128:129]
	v_lshl_add_u64 v[6:7], s[8:9], 0, v[134:135]
	s_cselect_b64 s[16:17], -1, 0
	s_cmp_lg_u32 s0, 1
	v_lshl_add_u64 v[10:11], s[8:9], 0, v[130:131]
	s_cbranch_scc1 .LBB0_1484
	s_barrier
